# XCD barrier leader also issues its L1 invalidate early, together with its L2 write-back, instead of right before releasing its followers
# speedup vs baseline: 1.0229x; 1.0007x over previous
.LBB0_192:
	s_andn2_saveexec_b64 s[0:1], s[0:1]
	s_cbranch_execz .LBB0_208
	v_mov_b32_e32 v1, s34
	v_add_co_u32_e32 v2, vcc, 0x3000, v1
	v_mov_b32_e32 v1, s35
	buffer_wbl2 sc1
	buffer_inv sc1
	s_nop 0
	s_nop 0
	s_nop 0
	s_nop 0
	s_nop 0
	s_nop 0
	s_nop 0
	s_nop 0
	s_nop 0
	s_nop 0
	s_nop 0
	s_nop 0
	s_nop 0
	s_nop 0
	s_waitcnt vmcnt(0)
	v_addc_co_u32_e32 v3, vcc, 0, v1, vcc
	v_mov_b32_e32 v1, 1
	flat_atomic_add v1, v[2:3], v1 offset:1024 sc0
	v_cvt_f32_u32_e32 v2, v0
	v_sub_u32_e32 v3, 0, v0
	s_add_u32 s0, s34, 0x3500
	s_addc_u32 s1, s35, 0
	v_rcp_iflag_f32_e32 v2, v2
	s_mov_b64 s[4:5], -1
	v_mul_f32_e32 v2, 0x4f7ffffe, v2
	v_cvt_u32_f32_e32 v2, v2
	v_mul_lo_u32 v3, v3, v2
	v_mul_hi_u32 v3, v2, v3
	v_add_u32_e32 v2, v2, v3
	s_waitcnt vmcnt(0) lgkmcnt(0)
	v_mul_hi_u32 v2, v1, v2
	v_mul_lo_u32 v4, v2, v0
	v_add_u32_e32 v3, 1, v1
	v_sub_u32_e32 v1, v1, v4
	v_add_u32_e32 v5, 1, v2
	v_cmp_ge_u32_e32 vcc, v1, v0
	v_sub_u32_e32 v4, v1, v0
	s_nop 0
	v_cndmask_b32_e32 v2, v2, v5, vcc
	v_cndmask_b32_e32 v1, v1, v4, vcc
	v_add_u32_e32 v4, 1, v2
	v_cmp_ge_u32_e32 vcc, v1, v0
	s_nop 1
	v_cndmask_b32_e32 v2, v2, v4, vcc
	v_mad_u64_u32 v[0:1], s[2:3], v0, v2, v[0:1]
	v_cmp_ne_u32_e32 vcc, v3, v0
	v_mov_b64_e32 v[0:1], s[0:1]
	s_and_saveexec_b64 s[2:3], vcc
	s_cbranch_execz .LBB0_205
	v_mov_b64_e32 v[0:1], s[0:1]
	global_load_dword v0, v[0:1], off sc1
	s_mov_b64 s[8:9], 0
	s_waitcnt vmcnt(0) lgkmcnt(0)
	v_cmp_eq_u32_e32 vcc, v0, v2
	s_and_saveexec_b64 s[6:7], vcc
	s_cbranch_execz .LBB0_204
	s_add_u32 s4, s34, 0x200
	s_addc_u32 s5, s35, 0
	s_mov_b32 s21, 1
	s_branch .LBB0_197

.LBB0_207:
	s_or_b64 exec, exec, s[0:1]
	s_add_i32 s0, s20, 0x900
	s_mov_b32 s1, 0
	s_lshl_b64 s[0:1], s[0:1], 2
	s_add_u32 s0, s34, s0
	s_addc_u32 s1, s35, s1
	v_mov_b32_e32 v2, 1
	v_mov_b64_e32 v[0:1], s[0:1]
	s_waitcnt vmcnt(0) lgkmcnt(0)
	s_nop 0
	s_nop 0
	flat_atomic_add v[0:1], v2
	s_waitcnt vmcnt(0)

.LBB0_256:
	s_andn2_saveexec_b64 s[0:1], s[0:1]
	s_cbranch_execz .LBB0_272
	v_mov_b32_e32 v1, s34
	v_add_co_u32_e32 v2, vcc, 0x3000, v1
	v_mov_b32_e32 v1, s35
	buffer_wbl2 sc1
	buffer_inv sc1
	s_nop 0
	s_nop 0
	s_nop 0
	s_nop 0
	s_nop 0
	s_nop 0
	s_nop 0
	s_nop 0
	s_nop 0
	s_nop 0
	s_nop 0
	s_nop 0
	s_nop 0
	s_nop 0
	s_waitcnt vmcnt(0)
	v_addc_co_u32_e32 v3, vcc, 0, v1, vcc
	flat_atomic_add v1, v[2:3], v171 offset:1024 sc0
	v_cvt_f32_u32_e32 v2, v0
	v_sub_u32_e32 v3, 0, v0
	s_mov_b64 s[4:5], -1
	v_rcp_iflag_f32_e32 v2, v2
	s_nop 0
	v_mul_f32_e32 v2, 0x4f7ffffe, v2
	v_cvt_u32_f32_e32 v2, v2
	v_mul_lo_u32 v3, v3, v2
	v_mul_hi_u32 v3, v2, v3
	v_add_u32_e32 v2, v2, v3
	s_waitcnt vmcnt(0) lgkmcnt(0)
	v_mul_hi_u32 v2, v1, v2
	v_mul_lo_u32 v3, v2, v0
	v_sub_u32_e32 v3, v1, v3
	v_cmp_ge_u32_e32 vcc, v3, v0
	v_add_u32_e32 v4, 1, v2
	s_nop 0
	v_cndmask_b32_e32 v2, v2, v4, vcc
	v_sub_u32_e32 v4, v3, v0
	v_cndmask_b32_e32 v3, v3, v4, vcc
	v_cmp_ge_u32_e32 vcc, v3, v0
	v_add_u32_e32 v3, 1, v2
	s_nop 0
	v_cndmask_b32_e32 v2, v2, v3, vcc
	v_add_u32_e32 v3, 1, v1
	v_mad_u64_u32 v[0:1], s[0:1], v0, v2, v[0:1]
	s_add_u32 s0, s34, 0x3500
	s_addc_u32 s1, s35, 0
	v_cmp_ne_u32_e32 vcc, v3, v0
	v_mov_b64_e32 v[0:1], s[0:1]
	s_and_saveexec_b64 s[2:3], vcc
	s_cbranch_execz .LBB0_269
	v_mov_b64_e32 v[0:1], s[0:1]
	global_load_dword v0, v[0:1], off sc1
	s_mov_b64 s[8:9], 0
	s_waitcnt vmcnt(0) lgkmcnt(0)
	v_cmp_eq_u32_e32 vcc, v0, v2
	s_and_saveexec_b64 s[6:7], vcc
	s_cbranch_execz .LBB0_268
	s_add_u32 s4, s34, 0x200
	s_addc_u32 s5, s35, 0
	s_mov_b32 s21, 1
	s_branch .LBB0_261

.LBB0_271:
	s_or_b64 exec, exec, s[0:1]
	s_add_i32 s84, s20, 0x900
	s_lshl_b64 s[0:1], s[84:85], 2
	s_add_u32 s0, s34, s0
	s_addc_u32 s1, s35, s1
	v_mov_b64_e32 v[0:1], s[0:1]
	s_waitcnt vmcnt(0) lgkmcnt(0)
	s_nop 0
	s_nop 0
	flat_atomic_add v[0:1], v171
	s_waitcnt vmcnt(0)

.LBB0_772:
	s_andn2_saveexec_b64 s[0:1], s[0:1]
	s_cbranch_execz .LBB0_788
	v_mov_b32_e32 v1, s36
	v_add_co_u32_e32 v2, vcc, 0x3000, v1
	v_mov_b32_e32 v1, s37
	buffer_wbl2 sc1
	buffer_inv sc1
	s_nop 0
	s_nop 0
	s_nop 0
	s_nop 0
	s_nop 0
	s_nop 0
	s_nop 0
	s_nop 0
	s_nop 0
	s_nop 0
	s_nop 0
	s_nop 0
	s_nop 0
	s_nop 0
	s_waitcnt vmcnt(0)
	v_addc_co_u32_e32 v3, vcc, 0, v1, vcc
	flat_atomic_add v1, v[2:3], v171 offset:1024 sc0
	v_cvt_f32_u32_e32 v2, v0
	v_sub_u32_e32 v3, 0, v0
	s_mov_b64 s[4:5], -1
	v_rcp_iflag_f32_e32 v2, v2
	s_nop 0
	v_mul_f32_e32 v2, 0x4f7ffffe, v2
	v_cvt_u32_f32_e32 v2, v2
	v_mul_lo_u32 v3, v3, v2
	v_mul_hi_u32 v3, v2, v3
	v_add_u32_e32 v2, v2, v3
	s_waitcnt vmcnt(0) lgkmcnt(0)
	v_mul_hi_u32 v2, v1, v2
	v_mul_lo_u32 v3, v2, v0
	v_sub_u32_e32 v3, v1, v3
	v_cmp_ge_u32_e32 vcc, v3, v0
	v_add_u32_e32 v4, 1, v2
	s_nop 0
	v_cndmask_b32_e32 v2, v2, v4, vcc
	v_sub_u32_e32 v4, v3, v0
	v_cndmask_b32_e32 v3, v3, v4, vcc
	v_cmp_ge_u32_e32 vcc, v3, v0
	v_add_u32_e32 v3, 1, v2
	s_nop 0
	v_cndmask_b32_e32 v2, v2, v3, vcc
	v_add_u32_e32 v3, 1, v1
	v_mad_u64_u32 v[0:1], s[0:1], v0, v2, v[0:1]
	s_add_u32 s0, s36, 0x3500
	s_addc_u32 s1, s37, 0
	v_cmp_ne_u32_e32 vcc, v3, v0
	v_mov_b64_e32 v[0:1], s[0:1]
	s_and_saveexec_b64 s[2:3], vcc
	s_cbranch_execz .LBB0_785
	v_mov_b64_e32 v[0:1], s[0:1]
	global_load_dword v0, v[0:1], off sc1
	s_mov_b64 s[8:9], 0
	s_waitcnt vmcnt(0) lgkmcnt(0)
	v_cmp_eq_u32_e32 vcc, v0, v2
	s_and_saveexec_b64 s[6:7], vcc
	s_cbranch_execz .LBB0_784
	s_add_u32 s4, s36, 0x200
	s_addc_u32 s5, s37, 0
	s_mov_b32 s21, 1
	s_branch .LBB0_777

.LBB0_787:
	s_or_b64 exec, exec, s[0:1]
	s_add_i32 s84, s20, 0x900
	s_lshl_b64 s[0:1], s[84:85], 2
	s_add_u32 s0, s36, s0
	s_addc_u32 s1, s37, s1
	v_mov_b64_e32 v[0:1], s[0:1]
	s_waitcnt vmcnt(0) lgkmcnt(0)
	s_nop 0
	s_nop 0
	flat_atomic_add v[0:1], v171
	s_waitcnt vmcnt(0)
